# build_cum gate loops (r1, r3): 16 serialized load-wait-compute rounds replaced by one prefetched burst with progressive vmcnt waits
# speedup vs baseline: 1.0198x; 1.0072x over previous
; __device__ __forceinline__ float logsigmoidf(float x) { return fminf(x, 0.f) - __logf(1.f + __expf(-fabsf(x))); }
; __device__ __forceinline__ void build_cum(const Args& a, int L, int hl, long R0, const bf16_t* __restrict__ proj, LAS unsigned char* lds) {
;     ...
; #pragma unroll 4
;         for (int it = 0; it < 16; ++it) { const int i = isub + 4 * it; const bf16_t* ga = proj + (R0 + i) * LD + GAF + dir * 16;
;             const u32x4 g0 = *(const u32x4*)ga, g1 = *(const u32x4*)(ga + 8);
;             float x = gb;
;             x += gw[0] * bflo(g0.x) + gw[1] * bfhi(g0.x) + gw[2] * bflo(g0.y) + gw[3] * bfhi(g0.y) + gw[4] * bflo(g0.z) + gw[5] * bfhi(g0.z) + gw[6] * bflo(g0.w) + gw[7] * bfhi(g0.w);
;             x += gw[8] * bflo(g1.x) + gw[9] * bfhi(g1.x) + gw[10] * bflo(g1.y) + gw[11] * bfhi(g1.y) + gw[12] * bflo(g1.z) + gw[13] * bfhi(g1.z) + gw[14] * bflo(g1.w) + gw[15] * bfhi(g1.w);
;             cum[(dir * 64 + i) * 64 + k] = logsigmoidf(x) * (1.0f / 16.0f); }
.LBB0_123:
	s_mov_b32 s10, 0x1af03000
	s_mov_b32 s11, 0
	v_lshl_add_u64 v[32:33], v[18:19], 0, s[10:11]
	s_mov_b32 s10, 0xc800
	global_load_dwordx4 v[52:55], v[32:33], off
	global_load_dwordx4 v[56:59], v[32:33], off offset:16
	v_lshl_add_u64 v[32:33], v[32:33], 0, s[10:11]
	global_load_dwordx4 v[60:63], v[32:33], off
	global_load_dwordx4 v[64:67], v[32:33], off offset:16
	v_lshl_add_u64 v[32:33], v[32:33], 0, s[10:11]
	global_load_dwordx4 v[68:71], v[32:33], off
	global_load_dwordx4 v[72:75], v[32:33], off offset:16
	v_lshl_add_u64 v[32:33], v[32:33], 0, s[10:11]
	global_load_dwordx4 v[76:79], v[32:33], off
	global_load_dwordx4 v[80:83], v[32:33], off offset:16
	v_lshl_add_u64 v[32:33], v[32:33], 0, s[10:11]
	global_load_dwordx4 v[84:87], v[32:33], off
	global_load_dwordx4 v[88:91], v[32:33], off offset:16
	v_lshl_add_u64 v[32:33], v[32:33], 0, s[10:11]
	global_load_dwordx4 v[92:95], v[32:33], off
	global_load_dwordx4 v[96:99], v[32:33], off offset:16
	v_lshl_add_u64 v[32:33], v[32:33], 0, s[10:11]
	global_load_dwordx4 v[100:103], v[32:33], off
	global_load_dwordx4 v[104:107], v[32:33], off offset:16
	v_lshl_add_u64 v[32:33], v[32:33], 0, s[10:11]
	global_load_dwordx4 v[108:111], v[32:33], off
	global_load_dwordx4 v[112:115], v[32:33], off offset:16
	v_lshl_add_u64 v[32:33], v[32:33], 0, s[10:11]
	global_load_dwordx4 v[116:119], v[32:33], off
	global_load_dwordx4 v[120:123], v[32:33], off offset:16
	v_lshl_add_u64 v[32:33], v[32:33], 0, s[10:11]
	global_load_dwordx4 v[124:127], v[32:33], off
	global_load_dwordx4 v[128:131], v[32:33], off offset:16
	v_lshl_add_u64 v[32:33], v[32:33], 0, s[10:11]
	global_load_dwordx4 v[132:135], v[32:33], off
	global_load_dwordx4 v[136:139], v[32:33], off offset:16
	v_lshl_add_u64 v[32:33], v[32:33], 0, s[10:11]
	global_load_dwordx4 v[140:143], v[32:33], off
	global_load_dwordx4 v[144:147], v[32:33], off offset:16
	v_lshl_add_u64 v[32:33], v[32:33], 0, s[10:11]
	global_load_dwordx4 v[148:151], v[32:33], off
	global_load_dwordx4 v[152:155], v[32:33], off offset:16
	v_lshl_add_u64 v[32:33], v[32:33], 0, s[10:11]
	global_load_dwordx4 v[156:159], v[32:33], off
	global_load_dwordx4 v[160:163], v[32:33], off offset:16
	v_lshl_add_u64 v[32:33], v[32:33], 0, s[10:11]
	global_load_dwordx4 v[164:167], v[32:33], off
	global_load_dwordx4 v[168:171], v[32:33], off offset:16
	v_lshl_add_u64 v[32:33], v[32:33], 0, s[10:11]
	s_waitcnt vmcnt(28)
	v_and_b32_e32 v38, 0xffff0000, v52
	v_and_b32_e32 v39, 0xffff0000, v56
	v_lshlrev_b32_e32 v37, 16, v56
	v_lshlrev_b32_e32 v36, 16, v52
	v_pk_mul_f32 v[38:39], v[4:5], v[38:39]
	v_and_b32_e32 v30, 0xffff0000, v53
	v_pk_fma_f32 v[36:37], v[2:3], v[36:37], v[38:39]
	v_lshlrev_b32_e32 v39, 16, v57
	v_lshlrev_b32_e32 v38, 16, v53
	v_pk_fma_f32 v[36:37], v[6:7], v[38:39], v[36:37]
	v_and_b32_e32 v31, 0xffff0000, v57
	v_pk_fma_f32 v[26:27], v[8:9], v[30:31], v[36:37]
	v_lshlrev_b32_e32 v31, 16, v58
	v_lshlrev_b32_e32 v30, 16, v54
	v_pk_fma_f32 v[26:27], v[10:11], v[30:31], v[26:27]
	v_and_b32_e32 v31, 0xffff0000, v58
	v_and_b32_e32 v30, 0xffff0000, v54
	v_pk_fma_f32 v[26:27], v[12:13], v[30:31], v[26:27]
	v_lshlrev_b32_e32 v31, 16, v59
	v_lshlrev_b32_e32 v30, 16, v55
	v_pk_fma_f32 v[26:27], v[14:15], v[30:31], v[26:27]
	v_and_b32_e32 v31, 0xffff0000, v59
	v_and_b32_e32 v30, 0xffff0000, v55
	v_pk_fma_f32 v[26:27], v[16:17], v[30:31], v[26:27]
	s_nop 0
	v_add_f32_e32 v23, v22, v26
	v_add_f32_e32 v23, v23, v27
	v_min_f32_e32 v25, 0, v23
	v_mul_f32_e64 v23, |v23|, s95
	v_exp_f32_e32 v23, v23
	s_nop 0
	v_add_f32_e32 v23, 1.0, v23
	v_cmp_gt_f32_e32 vcc, s34, v23
	s_nop 1
	v_cndmask_b32_e64 v26, 0, 32, vcc
	v_ldexp_f32 v23, v23, v26
	v_log_f32_e32 v23, v23
	s_nop 0
	v_mul_f32_e32 v26, 0x3f317217, v23
	v_fma_f32 v26, v23, s35, -v26
	v_fmac_f32_e32 v26, 0x3377d1cf, v23
	v_fmac_f32_e32 v26, 0x3f317217, v23
	v_cmp_lt_f32_e64 s[0:1], |v23|, s73
	s_nop 1
	v_cndmask_b32_e64 v23, v23, v26, s[0:1]
	v_cndmask_b32_e32 v26, 0, v210, vcc
	v_sub_f32_e32 v23, v23, v26
	v_sub_f32_e32 v23, v25, v23
	v_mul_f32_e32 v28, 0x3d800000, v23
	global_load_dwordx4 v[52:55], v[32:33], off
	global_load_dwordx4 v[56:59], v[32:33], off offset:16
	s_waitcnt vmcnt(28)
	v_and_b32_e32 v38, 0xffff0000, v60
	v_and_b32_e32 v39, 0xffff0000, v64
	v_lshlrev_b32_e32 v37, 16, v64
	v_lshlrev_b32_e32 v36, 16, v60
	v_pk_mul_f32 v[38:39], v[4:5], v[38:39]
	v_and_b32_e32 v30, 0xffff0000, v61
	v_pk_fma_f32 v[36:37], v[2:3], v[36:37], v[38:39]
	v_lshlrev_b32_e32 v39, 16, v65
	v_lshlrev_b32_e32 v38, 16, v61
	v_pk_fma_f32 v[36:37], v[6:7], v[38:39], v[36:37]
	v_and_b32_e32 v31, 0xffff0000, v65
	v_pk_fma_f32 v[26:27], v[8:9], v[30:31], v[36:37]
	v_lshlrev_b32_e32 v31, 16, v66
	v_lshlrev_b32_e32 v30, 16, v62
	v_pk_fma_f32 v[26:27], v[10:11], v[30:31], v[26:27]
	v_and_b32_e32 v31, 0xffff0000, v66
	v_and_b32_e32 v30, 0xffff0000, v62
	v_pk_fma_f32 v[26:27], v[12:13], v[30:31], v[26:27]
	v_lshlrev_b32_e32 v31, 16, v67
	v_lshlrev_b32_e32 v30, 16, v63
	v_pk_fma_f32 v[26:27], v[14:15], v[30:31], v[26:27]
	v_and_b32_e32 v31, 0xffff0000, v67
	v_and_b32_e32 v30, 0xffff0000, v63
	v_pk_fma_f32 v[26:27], v[16:17], v[30:31], v[26:27]
	s_nop 0
	v_add_f32_e32 v23, v22, v26
	v_add_f32_e32 v23, v23, v27
	v_min_f32_e32 v25, 0, v23
	v_mul_f32_e64 v23, |v23|, s95
	v_exp_f32_e32 v23, v23
	s_nop 0
	v_add_f32_e32 v23, 1.0, v23
	v_cmp_gt_f32_e32 vcc, s34, v23
	s_nop 1
	v_cndmask_b32_e64 v26, 0, 32, vcc
	v_ldexp_f32 v23, v23, v26
	v_log_f32_e32 v23, v23
	s_nop 0
	v_mul_f32_e32 v26, 0x3f317217, v23
	v_fma_f32 v26, v23, s35, -v26
	v_fmac_f32_e32 v26, 0x3377d1cf, v23
	v_fmac_f32_e32 v26, 0x3f317217, v23
	v_cmp_lt_f32_e64 s[0:1], |v23|, s73
	s_nop 1
	v_cndmask_b32_e64 v23, v23, v26, s[0:1]
	v_cndmask_b32_e32 v26, 0, v210, vcc
	v_sub_f32_e32 v23, v23, v26
	v_sub_f32_e32 v23, v25, v23
	v_mul_f32_e32 v29, 0x3d800000, v23
	ds_write2st64_b32 v0, v28, v29 offset1:4
	s_waitcnt vmcnt(26)
; __device__ __forceinline__ float logsigmoidf(float x) { return fminf(x, 0.f) - __logf(1.f + __expf(-fabsf(x))); }
; __device__ __forceinline__ void build_cum(const Args& a, int L, int hl, long R0, const bf16_t* __restrict__ proj, LAS unsigned char* lds) {
;     ...
;         for (int it = 0; it < 16; ++it) { const int i = isub + 4 * it; const bf16_t* ga = proj + (R0 + i) * LD + GAF + dir * 16;
;             const u32x4 g0 = *(const u32x4*)ga, g1 = *(const u32x4*)(ga + 8);
;             float x = gb;
;             x += gw[0] * bflo(g0.x) + gw[1] * bfhi(g0.x) + gw[2] * bflo(g0.y) + gw[3] * bfhi(g0.y) + gw[4] * bflo(g0.z) + gw[5] * bfhi(g0.z) + gw[6] * bflo(g0.w) + gw[7] * bfhi(g0.w);
;             x += gw[8] * bflo(g1.x) + gw[9] * bfhi(g1.x) + gw[10] * bflo(g1.y) + gw[11] * bfhi(g1.y) + gw[12] * bflo(g1.z) + gw[13] * bfhi(g1.z) + gw[14] * bflo(g1.w) + gw[15] * bfhi(g1.w);
;             cum[(dir * 64 + i) * 64 + k] = logsigmoidf(x) * (1.0f / 16.0f); }
	v_and_b32_e32 v38, 0xffff0000, v68
	v_and_b32_e32 v39, 0xffff0000, v72
	v_lshlrev_b32_e32 v37, 16, v72
	v_lshlrev_b32_e32 v36, 16, v68
	v_pk_mul_f32 v[38:39], v[4:5], v[38:39]
	v_and_b32_e32 v30, 0xffff0000, v69
	v_pk_fma_f32 v[36:37], v[2:3], v[36:37], v[38:39]
	v_lshlrev_b32_e32 v39, 16, v73
	v_lshlrev_b32_e32 v38, 16, v69
	v_pk_fma_f32 v[36:37], v[6:7], v[38:39], v[36:37]
	v_and_b32_e32 v31, 0xffff0000, v73
	v_pk_fma_f32 v[26:27], v[8:9], v[30:31], v[36:37]
	v_lshlrev_b32_e32 v31, 16, v74
	v_lshlrev_b32_e32 v30, 16, v70
	v_pk_fma_f32 v[26:27], v[10:11], v[30:31], v[26:27]
	v_and_b32_e32 v31, 0xffff0000, v74
	v_and_b32_e32 v30, 0xffff0000, v70
	v_pk_fma_f32 v[26:27], v[12:13], v[30:31], v[26:27]
	v_lshlrev_b32_e32 v31, 16, v75
	v_lshlrev_b32_e32 v30, 16, v71
	v_pk_fma_f32 v[26:27], v[14:15], v[30:31], v[26:27]
	v_and_b32_e32 v31, 0xffff0000, v75
	v_and_b32_e32 v30, 0xffff0000, v71
	v_pk_fma_f32 v[26:27], v[16:17], v[30:31], v[26:27]
	s_nop 0
	v_add_f32_e32 v23, v22, v26
	v_add_f32_e32 v23, v23, v27
	v_min_f32_e32 v25, 0, v23
	v_mul_f32_e64 v23, |v23|, s95
	v_exp_f32_e32 v23, v23
	s_nop 0
	v_add_f32_e32 v23, 1.0, v23
	v_cmp_gt_f32_e32 vcc, s34, v23
	s_nop 1
	v_cndmask_b32_e64 v26, 0, 32, vcc
	v_ldexp_f32 v23, v23, v26
	v_log_f32_e32 v23, v23
	s_nop 0
	v_mul_f32_e32 v26, 0x3f317217, v23
	v_fma_f32 v26, v23, s35, -v26
	v_fmac_f32_e32 v26, 0x3377d1cf, v23
	v_fmac_f32_e32 v26, 0x3f317217, v23
	v_cmp_lt_f32_e64 s[0:1], |v23|, s73
	s_nop 1
	v_cndmask_b32_e64 v23, v23, v26, s[0:1]
	v_cndmask_b32_e32 v26, 0, v210, vcc
	v_sub_f32_e32 v23, v23, v26
	v_sub_f32_e32 v23, v25, v23
	v_mul_f32_e32 v28, 0x3d800000, v23
	s_waitcnt vmcnt(24)
	v_and_b32_e32 v38, 0xffff0000, v76
	v_and_b32_e32 v39, 0xffff0000, v80
	v_lshlrev_b32_e32 v37, 16, v80
	v_lshlrev_b32_e32 v36, 16, v76
	v_pk_mul_f32 v[38:39], v[4:5], v[38:39]
	v_and_b32_e32 v30, 0xffff0000, v77
	v_pk_fma_f32 v[36:37], v[2:3], v[36:37], v[38:39]
	v_lshlrev_b32_e32 v39, 16, v81
	v_lshlrev_b32_e32 v38, 16, v77
	v_pk_fma_f32 v[36:37], v[6:7], v[38:39], v[36:37]
	v_and_b32_e32 v31, 0xffff0000, v81
	v_pk_fma_f32 v[26:27], v[8:9], v[30:31], v[36:37]
	v_lshlrev_b32_e32 v31, 16, v82
	v_lshlrev_b32_e32 v30, 16, v78
	v_pk_fma_f32 v[26:27], v[10:11], v[30:31], v[26:27]
	v_and_b32_e32 v31, 0xffff0000, v82
	v_and_b32_e32 v30, 0xffff0000, v78
	v_pk_fma_f32 v[26:27], v[12:13], v[30:31], v[26:27]
	v_lshlrev_b32_e32 v31, 16, v83
	v_lshlrev_b32_e32 v30, 16, v79
	v_pk_fma_f32 v[26:27], v[14:15], v[30:31], v[26:27]
	v_and_b32_e32 v31, 0xffff0000, v83
	v_and_b32_e32 v30, 0xffff0000, v79
	v_pk_fma_f32 v[26:27], v[16:17], v[30:31], v[26:27]
	s_nop 0
	v_add_f32_e32 v23, v22, v26
	v_add_f32_e32 v23, v23, v27
	v_min_f32_e32 v25, 0, v23
	v_mul_f32_e64 v23, |v23|, s95
	v_exp_f32_e32 v23, v23
	s_nop 0
	v_add_f32_e32 v23, 1.0, v23
	v_cmp_gt_f32_e32 vcc, s34, v23
	s_nop 1
	v_cndmask_b32_e64 v26, 0, 32, vcc
	v_ldexp_f32 v23, v23, v26
	v_log_f32_e32 v23, v23
	s_nop 0
	v_mul_f32_e32 v26, 0x3f317217, v23
	v_fma_f32 v26, v23, s35, -v26
	v_fmac_f32_e32 v26, 0x3377d1cf, v23
	v_fmac_f32_e32 v26, 0x3f317217, v23
	v_cmp_lt_f32_e64 s[0:1], |v23|, s73
	s_nop 1
	v_cndmask_b32_e64 v23, v23, v26, s[0:1]
	v_cndmask_b32_e32 v26, 0, v210, vcc
	v_sub_f32_e32 v23, v23, v26
	v_sub_f32_e32 v23, v25, v23
	v_mul_f32_e32 v29, 0x3d800000, v23
	ds_write2st64_b32 v0, v28, v29 offset0:8 offset1:12
	v_add_u32_e32 v0, 0x1000, v0
	s_waitcnt vmcnt(22)
	v_and_b32_e32 v38, 0xffff0000, v84
	v_and_b32_e32 v39, 0xffff0000, v88
	v_lshlrev_b32_e32 v37, 16, v88
	v_lshlrev_b32_e32 v36, 16, v84
	v_pk_mul_f32 v[38:39], v[4:5], v[38:39]
	v_and_b32_e32 v30, 0xffff0000, v85
	v_pk_fma_f32 v[36:37], v[2:3], v[36:37], v[38:39]
	v_lshlrev_b32_e32 v39, 16, v89
	v_lshlrev_b32_e32 v38, 16, v85
	v_pk_fma_f32 v[36:37], v[6:7], v[38:39], v[36:37]
	v_and_b32_e32 v31, 0xffff0000, v89
	v_pk_fma_f32 v[26:27], v[8:9], v[30:31], v[36:37]
	v_lshlrev_b32_e32 v31, 16, v90
	v_lshlrev_b32_e32 v30, 16, v86
	v_pk_fma_f32 v[26:27], v[10:11], v[30:31], v[26:27]
	v_and_b32_e32 v31, 0xffff0000, v90
	v_and_b32_e32 v30, 0xffff0000, v86
	v_pk_fma_f32 v[26:27], v[12:13], v[30:31], v[26:27]
	v_lshlrev_b32_e32 v31, 16, v91
	v_lshlrev_b32_e32 v30, 16, v87
	v_pk_fma_f32 v[26:27], v[14:15], v[30:31], v[26:27]
	v_and_b32_e32 v31, 0xffff0000, v91
	v_and_b32_e32 v30, 0xffff0000, v87
	v_pk_fma_f32 v[26:27], v[16:17], v[30:31], v[26:27]
	s_nop 0
	v_add_f32_e32 v23, v22, v26
	v_add_f32_e32 v23, v23, v27
	v_min_f32_e32 v25, 0, v23
	v_mul_f32_e64 v23, |v23|, s95
	v_exp_f32_e32 v23, v23
	s_nop 0
	v_add_f32_e32 v23, 1.0, v23
	v_cmp_gt_f32_e32 vcc, s34, v23
	s_nop 1
	v_cndmask_b32_e64 v26, 0, 32, vcc
	v_ldexp_f32 v23, v23, v26
	v_log_f32_e32 v23, v23
	s_nop 0
	v_mul_f32_e32 v26, 0x3f317217, v23
	v_fma_f32 v26, v23, s35, -v26
	v_fmac_f32_e32 v26, 0x3377d1cf, v23
	v_fmac_f32_e32 v26, 0x3f317217, v23
	v_cmp_lt_f32_e64 s[0:1], |v23|, s73
	s_nop 1
	v_cndmask_b32_e64 v23, v23, v26, s[0:1]
	v_cndmask_b32_e32 v26, 0, v210, vcc
	v_sub_f32_e32 v23, v23, v26
	v_sub_f32_e32 v23, v25, v23
	v_mul_f32_e32 v28, 0x3d800000, v23
	s_waitcnt vmcnt(20)
; __device__ __forceinline__ float logsigmoidf(float x) { return fminf(x, 0.f) - __logf(1.f + __expf(-fabsf(x))); }
; __device__ __forceinline__ void build_cum(const Args& a, int L, int hl, long R0, const bf16_t* __restrict__ proj, LAS unsigned char* lds) {
;     ...
;         for (int it = 0; it < 16; ++it) { const int i = isub + 4 * it; const bf16_t* ga = proj + (R0 + i) * LD + GAF + dir * 16;
;             const u32x4 g0 = *(const u32x4*)ga, g1 = *(const u32x4*)(ga + 8);
;             float x = gb;
;             x += gw[0] * bflo(g0.x) + gw[1] * bfhi(g0.x) + gw[2] * bflo(g0.y) + gw[3] * bfhi(g0.y) + gw[4] * bflo(g0.z) + gw[5] * bfhi(g0.z) + gw[6] * bflo(g0.w) + gw[7] * bfhi(g0.w);
;             x += gw[8] * bflo(g1.x) + gw[9] * bfhi(g1.x) + gw[10] * bflo(g1.y) + gw[11] * bfhi(g1.y) + gw[12] * bflo(g1.z) + gw[13] * bfhi(g1.z) + gw[14] * bflo(g1.w) + gw[15] * bfhi(g1.w);
;             cum[(dir * 64 + i) * 64 + k] = logsigmoidf(x) * (1.0f / 16.0f); }
	v_and_b32_e32 v38, 0xffff0000, v92
	v_and_b32_e32 v39, 0xffff0000, v96
	v_lshlrev_b32_e32 v37, 16, v96
	v_lshlrev_b32_e32 v36, 16, v92
	v_pk_mul_f32 v[38:39], v[4:5], v[38:39]
	v_and_b32_e32 v30, 0xffff0000, v93
	v_pk_fma_f32 v[36:37], v[2:3], v[36:37], v[38:39]
	v_lshlrev_b32_e32 v39, 16, v97
	v_lshlrev_b32_e32 v38, 16, v93
	v_pk_fma_f32 v[36:37], v[6:7], v[38:39], v[36:37]
	v_and_b32_e32 v31, 0xffff0000, v97
	v_pk_fma_f32 v[26:27], v[8:9], v[30:31], v[36:37]
	v_lshlrev_b32_e32 v31, 16, v98
	v_lshlrev_b32_e32 v30, 16, v94
	v_pk_fma_f32 v[26:27], v[10:11], v[30:31], v[26:27]
	v_and_b32_e32 v31, 0xffff0000, v98
	v_and_b32_e32 v30, 0xffff0000, v94
	v_pk_fma_f32 v[26:27], v[12:13], v[30:31], v[26:27]
	v_lshlrev_b32_e32 v31, 16, v99
	v_lshlrev_b32_e32 v30, 16, v95
	v_pk_fma_f32 v[26:27], v[14:15], v[30:31], v[26:27]
	v_and_b32_e32 v31, 0xffff0000, v99
	v_and_b32_e32 v30, 0xffff0000, v95
	v_pk_fma_f32 v[26:27], v[16:17], v[30:31], v[26:27]
	s_nop 0
	v_add_f32_e32 v23, v22, v26
	v_add_f32_e32 v23, v23, v27
	v_min_f32_e32 v25, 0, v23
	v_mul_f32_e64 v23, |v23|, s95
	v_exp_f32_e32 v23, v23
	s_nop 0
	v_add_f32_e32 v23, 1.0, v23
	v_cmp_gt_f32_e32 vcc, s34, v23
	s_nop 1
	v_cndmask_b32_e64 v26, 0, 32, vcc
	v_ldexp_f32 v23, v23, v26
	v_log_f32_e32 v23, v23
	s_nop 0
	v_mul_f32_e32 v26, 0x3f317217, v23
	v_fma_f32 v26, v23, s35, -v26
	v_fmac_f32_e32 v26, 0x3377d1cf, v23
	v_fmac_f32_e32 v26, 0x3f317217, v23
	v_cmp_lt_f32_e64 s[0:1], |v23|, s73
	s_nop 1
	v_cndmask_b32_e64 v23, v23, v26, s[0:1]
	v_cndmask_b32_e32 v26, 0, v210, vcc
	v_sub_f32_e32 v23, v23, v26
	v_sub_f32_e32 v23, v25, v23
	v_mul_f32_e32 v29, 0x3d800000, v23
	ds_write2st64_b32 v0, v28, v29 offset1:4
	s_waitcnt vmcnt(18)
	v_and_b32_e32 v38, 0xffff0000, v100
	v_and_b32_e32 v39, 0xffff0000, v104
	v_lshlrev_b32_e32 v37, 16, v104
	v_lshlrev_b32_e32 v36, 16, v100
	v_pk_mul_f32 v[38:39], v[4:5], v[38:39]
	v_and_b32_e32 v30, 0xffff0000, v101
	v_pk_fma_f32 v[36:37], v[2:3], v[36:37], v[38:39]
	v_lshlrev_b32_e32 v39, 16, v105
	v_lshlrev_b32_e32 v38, 16, v101
	v_pk_fma_f32 v[36:37], v[6:7], v[38:39], v[36:37]
	v_and_b32_e32 v31, 0xffff0000, v105
	v_pk_fma_f32 v[26:27], v[8:9], v[30:31], v[36:37]
	v_lshlrev_b32_e32 v31, 16, v106
	v_lshlrev_b32_e32 v30, 16, v102
	v_pk_fma_f32 v[26:27], v[10:11], v[30:31], v[26:27]
	v_and_b32_e32 v31, 0xffff0000, v106
	v_and_b32_e32 v30, 0xffff0000, v102
	v_pk_fma_f32 v[26:27], v[12:13], v[30:31], v[26:27]
	v_lshlrev_b32_e32 v31, 16, v107
	v_lshlrev_b32_e32 v30, 16, v103
	v_pk_fma_f32 v[26:27], v[14:15], v[30:31], v[26:27]
	v_and_b32_e32 v31, 0xffff0000, v107
	v_and_b32_e32 v30, 0xffff0000, v103
	v_pk_fma_f32 v[26:27], v[16:17], v[30:31], v[26:27]
	s_nop 0
	v_add_f32_e32 v23, v22, v26
	v_add_f32_e32 v23, v23, v27
	v_min_f32_e32 v25, 0, v23
	v_mul_f32_e64 v23, |v23|, s95
	v_exp_f32_e32 v23, v23
	s_nop 0
	v_add_f32_e32 v23, 1.0, v23
	v_cmp_gt_f32_e32 vcc, s34, v23
	s_nop 1
	v_cndmask_b32_e64 v26, 0, 32, vcc
	v_ldexp_f32 v23, v23, v26
	v_log_f32_e32 v23, v23
	s_nop 0
	v_mul_f32_e32 v26, 0x3f317217, v23
	v_fma_f32 v26, v23, s35, -v26
	v_fmac_f32_e32 v26, 0x3377d1cf, v23
	v_fmac_f32_e32 v26, 0x3f317217, v23
	v_cmp_lt_f32_e64 s[0:1], |v23|, s73
	s_nop 1
	v_cndmask_b32_e64 v23, v23, v26, s[0:1]
	v_cndmask_b32_e32 v26, 0, v210, vcc
	v_sub_f32_e32 v23, v23, v26
	v_sub_f32_e32 v23, v25, v23
	v_mul_f32_e32 v28, 0x3d800000, v23
	s_waitcnt vmcnt(16)
	v_and_b32_e32 v38, 0xffff0000, v108
	v_and_b32_e32 v39, 0xffff0000, v112
	v_lshlrev_b32_e32 v37, 16, v112
	v_lshlrev_b32_e32 v36, 16, v108
	v_pk_mul_f32 v[38:39], v[4:5], v[38:39]
	v_and_b32_e32 v30, 0xffff0000, v109
	v_pk_fma_f32 v[36:37], v[2:3], v[36:37], v[38:39]
	v_lshlrev_b32_e32 v39, 16, v113
	v_lshlrev_b32_e32 v38, 16, v109
	v_pk_fma_f32 v[36:37], v[6:7], v[38:39], v[36:37]
	v_and_b32_e32 v31, 0xffff0000, v113
	v_pk_fma_f32 v[26:27], v[8:9], v[30:31], v[36:37]
	v_lshlrev_b32_e32 v31, 16, v114
	v_lshlrev_b32_e32 v30, 16, v110
	v_pk_fma_f32 v[26:27], v[10:11], v[30:31], v[26:27]
	v_and_b32_e32 v31, 0xffff0000, v114
	v_and_b32_e32 v30, 0xffff0000, v110
	v_pk_fma_f32 v[26:27], v[12:13], v[30:31], v[26:27]
	v_lshlrev_b32_e32 v31, 16, v115
	v_lshlrev_b32_e32 v30, 16, v111
	v_pk_fma_f32 v[26:27], v[14:15], v[30:31], v[26:27]
	v_and_b32_e32 v31, 0xffff0000, v115
	v_and_b32_e32 v30, 0xffff0000, v111
	v_pk_fma_f32 v[26:27], v[16:17], v[30:31], v[26:27]
	s_nop 0
	v_add_f32_e32 v23, v22, v26
	v_add_f32_e32 v23, v23, v27
	v_min_f32_e32 v25, 0, v23
	v_mul_f32_e64 v23, |v23|, s95
	v_exp_f32_e32 v23, v23
	s_nop 0
	v_add_f32_e32 v23, 1.0, v23
	v_cmp_gt_f32_e32 vcc, s34, v23
	s_nop 1
	v_cndmask_b32_e64 v26, 0, 32, vcc
	v_ldexp_f32 v23, v23, v26
	v_log_f32_e32 v23, v23
	s_nop 0
	v_mul_f32_e32 v26, 0x3f317217, v23
	v_fma_f32 v26, v23, s35, -v26
	v_fmac_f32_e32 v26, 0x3377d1cf, v23
	v_fmac_f32_e32 v26, 0x3f317217, v23
	v_cmp_lt_f32_e64 s[0:1], |v23|, s73
	s_nop 1
	v_cndmask_b32_e64 v23, v23, v26, s[0:1]
	v_cndmask_b32_e32 v26, 0, v210, vcc
	v_sub_f32_e32 v23, v23, v26
	v_sub_f32_e32 v23, v25, v23
	v_mul_f32_e32 v29, 0x3d800000, v23
	ds_write2st64_b32 v0, v28, v29 offset0:8 offset1:12
	v_add_u32_e32 v0, 0x1000, v0
	s_waitcnt vmcnt(14)
; __device__ __forceinline__ float logsigmoidf(float x) { return fminf(x, 0.f) - __logf(1.f + __expf(-fabsf(x))); }
; __device__ __forceinline__ void build_cum(const Args& a, int L, int hl, long R0, const bf16_t* __restrict__ proj, LAS unsigned char* lds) {
;     ...
;         for (int it = 0; it < 16; ++it) { const int i = isub + 4 * it; const bf16_t* ga = proj + (R0 + i) * LD + GAF + dir * 16;
;             const u32x4 g0 = *(const u32x4*)ga, g1 = *(const u32x4*)(ga + 8);
;             float x = gb;
;             x += gw[0] * bflo(g0.x) + gw[1] * bfhi(g0.x) + gw[2] * bflo(g0.y) + gw[3] * bfhi(g0.y) + gw[4] * bflo(g0.z) + gw[5] * bfhi(g0.z) + gw[6] * bflo(g0.w) + gw[7] * bfhi(g0.w);
;             x += gw[8] * bflo(g1.x) + gw[9] * bfhi(g1.x) + gw[10] * bflo(g1.y) + gw[11] * bfhi(g1.y) + gw[12] * bflo(g1.z) + gw[13] * bfhi(g1.z) + gw[14] * bflo(g1.w) + gw[15] * bfhi(g1.w);
;             cum[(dir * 64 + i) * 64 + k] = logsigmoidf(x) * (1.0f / 16.0f); }
	v_and_b32_e32 v38, 0xffff0000, v116
	v_and_b32_e32 v39, 0xffff0000, v120
	v_lshlrev_b32_e32 v37, 16, v120
	v_lshlrev_b32_e32 v36, 16, v116
	v_pk_mul_f32 v[38:39], v[4:5], v[38:39]
	v_and_b32_e32 v30, 0xffff0000, v117
	v_pk_fma_f32 v[36:37], v[2:3], v[36:37], v[38:39]
	v_lshlrev_b32_e32 v39, 16, v121
	v_lshlrev_b32_e32 v38, 16, v117
	v_pk_fma_f32 v[36:37], v[6:7], v[38:39], v[36:37]
	v_and_b32_e32 v31, 0xffff0000, v121
	v_pk_fma_f32 v[26:27], v[8:9], v[30:31], v[36:37]
	v_lshlrev_b32_e32 v31, 16, v122
	v_lshlrev_b32_e32 v30, 16, v118
	v_pk_fma_f32 v[26:27], v[10:11], v[30:31], v[26:27]
	v_and_b32_e32 v31, 0xffff0000, v122
	v_and_b32_e32 v30, 0xffff0000, v118
	v_pk_fma_f32 v[26:27], v[12:13], v[30:31], v[26:27]
	v_lshlrev_b32_e32 v31, 16, v123
	v_lshlrev_b32_e32 v30, 16, v119
	v_pk_fma_f32 v[26:27], v[14:15], v[30:31], v[26:27]
	v_and_b32_e32 v31, 0xffff0000, v123
	v_and_b32_e32 v30, 0xffff0000, v119
	v_pk_fma_f32 v[26:27], v[16:17], v[30:31], v[26:27]
	s_nop 0
	v_add_f32_e32 v23, v22, v26
	v_add_f32_e32 v23, v23, v27
	v_min_f32_e32 v25, 0, v23
	v_mul_f32_e64 v23, |v23|, s95
	v_exp_f32_e32 v23, v23
	s_nop 0
	v_add_f32_e32 v23, 1.0, v23
	v_cmp_gt_f32_e32 vcc, s34, v23
	s_nop 1
	v_cndmask_b32_e64 v26, 0, 32, vcc
	v_ldexp_f32 v23, v23, v26
	v_log_f32_e32 v23, v23
	s_nop 0
	v_mul_f32_e32 v26, 0x3f317217, v23
	v_fma_f32 v26, v23, s35, -v26
	v_fmac_f32_e32 v26, 0x3377d1cf, v23
	v_fmac_f32_e32 v26, 0x3f317217, v23
	v_cmp_lt_f32_e64 s[0:1], |v23|, s73
	s_nop 1
	v_cndmask_b32_e64 v23, v23, v26, s[0:1]
	v_cndmask_b32_e32 v26, 0, v210, vcc
	v_sub_f32_e32 v23, v23, v26
	v_sub_f32_e32 v23, v25, v23
	v_mul_f32_e32 v28, 0x3d800000, v23
	s_waitcnt vmcnt(12)
	v_and_b32_e32 v38, 0xffff0000, v124
	v_and_b32_e32 v39, 0xffff0000, v128
	v_lshlrev_b32_e32 v37, 16, v128
	v_lshlrev_b32_e32 v36, 16, v124
	v_pk_mul_f32 v[38:39], v[4:5], v[38:39]
	v_and_b32_e32 v30, 0xffff0000, v125
	v_pk_fma_f32 v[36:37], v[2:3], v[36:37], v[38:39]
	v_lshlrev_b32_e32 v39, 16, v129
	v_lshlrev_b32_e32 v38, 16, v125
	v_pk_fma_f32 v[36:37], v[6:7], v[38:39], v[36:37]
	v_and_b32_e32 v31, 0xffff0000, v129
	v_pk_fma_f32 v[26:27], v[8:9], v[30:31], v[36:37]
	v_lshlrev_b32_e32 v31, 16, v130
	v_lshlrev_b32_e32 v30, 16, v126
	v_pk_fma_f32 v[26:27], v[10:11], v[30:31], v[26:27]
	v_and_b32_e32 v31, 0xffff0000, v130
	v_and_b32_e32 v30, 0xffff0000, v126
	v_pk_fma_f32 v[26:27], v[12:13], v[30:31], v[26:27]
	v_lshlrev_b32_e32 v31, 16, v131
	v_lshlrev_b32_e32 v30, 16, v127
	v_pk_fma_f32 v[26:27], v[14:15], v[30:31], v[26:27]
	v_and_b32_e32 v31, 0xffff0000, v131
	v_and_b32_e32 v30, 0xffff0000, v127
	v_pk_fma_f32 v[26:27], v[16:17], v[30:31], v[26:27]
	s_nop 0
	v_add_f32_e32 v23, v22, v26
	v_add_f32_e32 v23, v23, v27
	v_min_f32_e32 v25, 0, v23
	v_mul_f32_e64 v23, |v23|, s95
	v_exp_f32_e32 v23, v23
	s_nop 0
	v_add_f32_e32 v23, 1.0, v23
	v_cmp_gt_f32_e32 vcc, s34, v23
	s_nop 1
	v_cndmask_b32_e64 v26, 0, 32, vcc
	v_ldexp_f32 v23, v23, v26
	v_log_f32_e32 v23, v23
	s_nop 0
	v_mul_f32_e32 v26, 0x3f317217, v23
	v_fma_f32 v26, v23, s35, -v26
	v_fmac_f32_e32 v26, 0x3377d1cf, v23
	v_fmac_f32_e32 v26, 0x3f317217, v23
	v_cmp_lt_f32_e64 s[0:1], |v23|, s73
	s_nop 1
	v_cndmask_b32_e64 v23, v23, v26, s[0:1]
	v_cndmask_b32_e32 v26, 0, v210, vcc
	v_sub_f32_e32 v23, v23, v26
	v_sub_f32_e32 v23, v25, v23
	v_mul_f32_e32 v29, 0x3d800000, v23
	ds_write2st64_b32 v0, v28, v29 offset1:4
	s_waitcnt vmcnt(10)
	v_and_b32_e32 v38, 0xffff0000, v132
	v_and_b32_e32 v39, 0xffff0000, v136
	v_lshlrev_b32_e32 v37, 16, v136
	v_lshlrev_b32_e32 v36, 16, v132
	v_pk_mul_f32 v[38:39], v[4:5], v[38:39]
	v_and_b32_e32 v30, 0xffff0000, v133
	v_pk_fma_f32 v[36:37], v[2:3], v[36:37], v[38:39]
	v_lshlrev_b32_e32 v39, 16, v137
	v_lshlrev_b32_e32 v38, 16, v133
	v_pk_fma_f32 v[36:37], v[6:7], v[38:39], v[36:37]
	v_and_b32_e32 v31, 0xffff0000, v137
	v_pk_fma_f32 v[26:27], v[8:9], v[30:31], v[36:37]
	v_lshlrev_b32_e32 v31, 16, v138
	v_lshlrev_b32_e32 v30, 16, v134
	v_pk_fma_f32 v[26:27], v[10:11], v[30:31], v[26:27]
	v_and_b32_e32 v31, 0xffff0000, v138
	v_and_b32_e32 v30, 0xffff0000, v134
	v_pk_fma_f32 v[26:27], v[12:13], v[30:31], v[26:27]
	v_lshlrev_b32_e32 v31, 16, v139
	v_lshlrev_b32_e32 v30, 16, v135
	v_pk_fma_f32 v[26:27], v[14:15], v[30:31], v[26:27]
	v_and_b32_e32 v31, 0xffff0000, v139
	v_and_b32_e32 v30, 0xffff0000, v135
	v_pk_fma_f32 v[26:27], v[16:17], v[30:31], v[26:27]
	s_nop 0
	v_add_f32_e32 v23, v22, v26
	v_add_f32_e32 v23, v23, v27
	v_min_f32_e32 v25, 0, v23
	v_mul_f32_e64 v23, |v23|, s95
	v_exp_f32_e32 v23, v23
	s_nop 0
	v_add_f32_e32 v23, 1.0, v23
	v_cmp_gt_f32_e32 vcc, s34, v23
	s_nop 1
	v_cndmask_b32_e64 v26, 0, 32, vcc
	v_ldexp_f32 v23, v23, v26
	v_log_f32_e32 v23, v23
	s_nop 0
	v_mul_f32_e32 v26, 0x3f317217, v23
	v_fma_f32 v26, v23, s35, -v26
	v_fmac_f32_e32 v26, 0x3377d1cf, v23
	v_fmac_f32_e32 v26, 0x3f317217, v23
	v_cmp_lt_f32_e64 s[0:1], |v23|, s73
	s_nop 1
	v_cndmask_b32_e64 v23, v23, v26, s[0:1]
	v_cndmask_b32_e32 v26, 0, v210, vcc
	v_sub_f32_e32 v23, v23, v26
	v_sub_f32_e32 v23, v25, v23
	v_mul_f32_e32 v28, 0x3d800000, v23
	s_waitcnt vmcnt(8)
; __device__ __forceinline__ float logsigmoidf(float x) { return fminf(x, 0.f) - __logf(1.f + __expf(-fabsf(x))); }
; __device__ __forceinline__ void build_cum(const Args& a, int L, int hl, long R0, const bf16_t* __restrict__ proj, LAS unsigned char* lds) {
;     ...
;         for (int it = 0; it < 16; ++it) { const int i = isub + 4 * it; const bf16_t* ga = proj + (R0 + i) * LD + GAF + dir * 16;
;             const u32x4 g0 = *(const u32x4*)ga, g1 = *(const u32x4*)(ga + 8);
;             float x = gb;
;             x += gw[0] * bflo(g0.x) + gw[1] * bfhi(g0.x) + gw[2] * bflo(g0.y) + gw[3] * bfhi(g0.y) + gw[4] * bflo(g0.z) + gw[5] * bfhi(g0.z) + gw[6] * bflo(g0.w) + gw[7] * bfhi(g0.w);
;             x += gw[8] * bflo(g1.x) + gw[9] * bfhi(g1.x) + gw[10] * bflo(g1.y) + gw[11] * bfhi(g1.y) + gw[12] * bflo(g1.z) + gw[13] * bfhi(g1.z) + gw[14] * bflo(g1.w) + gw[15] * bfhi(g1.w);
;             cum[(dir * 64 + i) * 64 + k] = logsigmoidf(x) * (1.0f / 16.0f); }
	v_and_b32_e32 v38, 0xffff0000, v140
	v_and_b32_e32 v39, 0xffff0000, v144
	v_lshlrev_b32_e32 v37, 16, v144
	v_lshlrev_b32_e32 v36, 16, v140
	v_pk_mul_f32 v[38:39], v[4:5], v[38:39]
	v_and_b32_e32 v30, 0xffff0000, v141
	v_pk_fma_f32 v[36:37], v[2:3], v[36:37], v[38:39]
	v_lshlrev_b32_e32 v39, 16, v145
	v_lshlrev_b32_e32 v38, 16, v141
	v_pk_fma_f32 v[36:37], v[6:7], v[38:39], v[36:37]
	v_and_b32_e32 v31, 0xffff0000, v145
	v_pk_fma_f32 v[26:27], v[8:9], v[30:31], v[36:37]
	v_lshlrev_b32_e32 v31, 16, v146
	v_lshlrev_b32_e32 v30, 16, v142
	v_pk_fma_f32 v[26:27], v[10:11], v[30:31], v[26:27]
	v_and_b32_e32 v31, 0xffff0000, v146
	v_and_b32_e32 v30, 0xffff0000, v142
	v_pk_fma_f32 v[26:27], v[12:13], v[30:31], v[26:27]
	v_lshlrev_b32_e32 v31, 16, v147
	v_lshlrev_b32_e32 v30, 16, v143
	v_pk_fma_f32 v[26:27], v[14:15], v[30:31], v[26:27]
	v_and_b32_e32 v31, 0xffff0000, v147
	v_and_b32_e32 v30, 0xffff0000, v143
	v_pk_fma_f32 v[26:27], v[16:17], v[30:31], v[26:27]
	s_nop 0
	v_add_f32_e32 v23, v22, v26
	v_add_f32_e32 v23, v23, v27
	v_min_f32_e32 v25, 0, v23
	v_mul_f32_e64 v23, |v23|, s95
	v_exp_f32_e32 v23, v23
	s_nop 0
	v_add_f32_e32 v23, 1.0, v23
	v_cmp_gt_f32_e32 vcc, s34, v23
	s_nop 1
	v_cndmask_b32_e64 v26, 0, 32, vcc
	v_ldexp_f32 v23, v23, v26
	v_log_f32_e32 v23, v23
	s_nop 0
	v_mul_f32_e32 v26, 0x3f317217, v23
	v_fma_f32 v26, v23, s35, -v26
	v_fmac_f32_e32 v26, 0x3377d1cf, v23
	v_fmac_f32_e32 v26, 0x3f317217, v23
	v_cmp_lt_f32_e64 s[0:1], |v23|, s73
	s_nop 1
	v_cndmask_b32_e64 v23, v23, v26, s[0:1]
	v_cndmask_b32_e32 v26, 0, v210, vcc
	v_sub_f32_e32 v23, v23, v26
	v_sub_f32_e32 v23, v25, v23
	v_mul_f32_e32 v29, 0x3d800000, v23
	ds_write2st64_b32 v0, v28, v29 offset0:8 offset1:12
	v_add_u32_e32 v0, 0x1000, v0
	s_waitcnt vmcnt(6)
	v_and_b32_e32 v38, 0xffff0000, v148
	v_and_b32_e32 v39, 0xffff0000, v152
	v_lshlrev_b32_e32 v37, 16, v152
	v_lshlrev_b32_e32 v36, 16, v148
	v_pk_mul_f32 v[38:39], v[4:5], v[38:39]
	v_and_b32_e32 v30, 0xffff0000, v149
	v_pk_fma_f32 v[36:37], v[2:3], v[36:37], v[38:39]
	v_lshlrev_b32_e32 v39, 16, v153
	v_lshlrev_b32_e32 v38, 16, v149
	v_pk_fma_f32 v[36:37], v[6:7], v[38:39], v[36:37]
	v_and_b32_e32 v31, 0xffff0000, v153
	v_pk_fma_f32 v[26:27], v[8:9], v[30:31], v[36:37]
	v_lshlrev_b32_e32 v31, 16, v154
	v_lshlrev_b32_e32 v30, 16, v150
	v_pk_fma_f32 v[26:27], v[10:11], v[30:31], v[26:27]
	v_and_b32_e32 v31, 0xffff0000, v154
	v_and_b32_e32 v30, 0xffff0000, v150
	v_pk_fma_f32 v[26:27], v[12:13], v[30:31], v[26:27]
	v_lshlrev_b32_e32 v31, 16, v155
	v_lshlrev_b32_e32 v30, 16, v151
	v_pk_fma_f32 v[26:27], v[14:15], v[30:31], v[26:27]
	v_and_b32_e32 v31, 0xffff0000, v155
	v_and_b32_e32 v30, 0xffff0000, v151
	v_pk_fma_f32 v[26:27], v[16:17], v[30:31], v[26:27]
	s_nop 0
	v_add_f32_e32 v23, v22, v26
	v_add_f32_e32 v23, v23, v27
	v_min_f32_e32 v25, 0, v23
	v_mul_f32_e64 v23, |v23|, s95
	v_exp_f32_e32 v23, v23
	s_nop 0
	v_add_f32_e32 v23, 1.0, v23
	v_cmp_gt_f32_e32 vcc, s34, v23
	s_nop 1
	v_cndmask_b32_e64 v26, 0, 32, vcc
	v_ldexp_f32 v23, v23, v26
	v_log_f32_e32 v23, v23
	s_nop 0
	v_mul_f32_e32 v26, 0x3f317217, v23
	v_fma_f32 v26, v23, s35, -v26
	v_fmac_f32_e32 v26, 0x3377d1cf, v23
	v_fmac_f32_e32 v26, 0x3f317217, v23
	v_cmp_lt_f32_e64 s[0:1], |v23|, s73
	s_nop 1
	v_cndmask_b32_e64 v23, v23, v26, s[0:1]
	v_cndmask_b32_e32 v26, 0, v210, vcc
	v_sub_f32_e32 v23, v23, v26
	v_sub_f32_e32 v23, v25, v23
	v_mul_f32_e32 v28, 0x3d800000, v23
	s_waitcnt vmcnt(4)
; __device__ __forceinline__ float logsigmoidf(float x) { return fminf(x, 0.f) - __logf(1.f + __expf(-fabsf(x))); }
; __device__ __forceinline__ void build_cum(const Args& a, int L, int hl, long R0, const bf16_t* __restrict__ proj, LAS unsigned char* lds) {
;     ...
;         for (int it = 0; it < 16; ++it) { const int i = isub + 4 * it; const bf16_t* ga = proj + (R0 + i) * LD + GAF + dir * 16;
;             const u32x4 g0 = *(const u32x4*)ga, g1 = *(const u32x4*)(ga + 8);
;             float x = gb;
;             x += gw[0] * bflo(g0.x) + gw[1] * bfhi(g0.x) + gw[2] * bflo(g0.y) + gw[3] * bfhi(g0.y) + gw[4] * bflo(g0.z) + gw[5] * bfhi(g0.z) + gw[6] * bflo(g0.w) + gw[7] * bfhi(g0.w);
;             x += gw[8] * bflo(g1.x) + gw[9] * bfhi(g1.x) + gw[10] * bflo(g1.y) + gw[11] * bfhi(g1.y) + gw[12] * bflo(g1.z) + gw[13] * bfhi(g1.z) + gw[14] * bflo(g1.w) + gw[15] * bfhi(g1.w);
;             cum[(dir * 64 + i) * 64 + k] = logsigmoidf(x) * (1.0f / 16.0f); }
	v_and_b32_e32 v38, 0xffff0000, v156
	v_and_b32_e32 v39, 0xffff0000, v160
	v_lshlrev_b32_e32 v37, 16, v160
	v_lshlrev_b32_e32 v36, 16, v156
	v_pk_mul_f32 v[38:39], v[4:5], v[38:39]
	v_and_b32_e32 v30, 0xffff0000, v157
	v_pk_fma_f32 v[36:37], v[2:3], v[36:37], v[38:39]
	v_lshlrev_b32_e32 v39, 16, v161
	v_lshlrev_b32_e32 v38, 16, v157
	v_pk_fma_f32 v[36:37], v[6:7], v[38:39], v[36:37]
	v_and_b32_e32 v31, 0xffff0000, v161
	v_pk_fma_f32 v[26:27], v[8:9], v[30:31], v[36:37]
	v_lshlrev_b32_e32 v31, 16, v162
	v_lshlrev_b32_e32 v30, 16, v158
	v_pk_fma_f32 v[26:27], v[10:11], v[30:31], v[26:27]
	v_and_b32_e32 v31, 0xffff0000, v162
	v_and_b32_e32 v30, 0xffff0000, v158
	v_pk_fma_f32 v[26:27], v[12:13], v[30:31], v[26:27]
	v_lshlrev_b32_e32 v31, 16, v163
	v_lshlrev_b32_e32 v30, 16, v159
	v_pk_fma_f32 v[26:27], v[14:15], v[30:31], v[26:27]
	v_and_b32_e32 v31, 0xffff0000, v163
	v_and_b32_e32 v30, 0xffff0000, v159
	v_pk_fma_f32 v[26:27], v[16:17], v[30:31], v[26:27]
	s_nop 0
	v_add_f32_e32 v23, v22, v26
	v_add_f32_e32 v23, v23, v27
	v_min_f32_e32 v25, 0, v23
	v_mul_f32_e64 v23, |v23|, s95
	v_exp_f32_e32 v23, v23
	s_nop 0
	v_add_f32_e32 v23, 1.0, v23
	v_cmp_gt_f32_e32 vcc, s34, v23
	s_nop 1
	v_cndmask_b32_e64 v26, 0, 32, vcc
	v_ldexp_f32 v23, v23, v26
	v_log_f32_e32 v23, v23
	s_nop 0
	v_mul_f32_e32 v26, 0x3f317217, v23
	v_fma_f32 v26, v23, s35, -v26
	v_fmac_f32_e32 v26, 0x3377d1cf, v23
	v_fmac_f32_e32 v26, 0x3f317217, v23
	v_cmp_lt_f32_e64 s[0:1], |v23|, s73
	s_nop 1
	v_cndmask_b32_e64 v23, v23, v26, s[0:1]
	v_cndmask_b32_e32 v26, 0, v210, vcc
	v_sub_f32_e32 v23, v23, v26
	v_sub_f32_e32 v23, v25, v23
	v_mul_f32_e32 v29, 0x3d800000, v23
	ds_write2st64_b32 v0, v28, v29 offset1:4
	s_waitcnt vmcnt(2)
	v_and_b32_e32 v38, 0xffff0000, v164
	v_and_b32_e32 v39, 0xffff0000, v168
	v_lshlrev_b32_e32 v37, 16, v168
	v_lshlrev_b32_e32 v36, 16, v164
	v_pk_mul_f32 v[38:39], v[4:5], v[38:39]
	v_and_b32_e32 v30, 0xffff0000, v165
	v_pk_fma_f32 v[36:37], v[2:3], v[36:37], v[38:39]
	v_lshlrev_b32_e32 v39, 16, v169
	v_lshlrev_b32_e32 v38, 16, v165
	v_pk_fma_f32 v[36:37], v[6:7], v[38:39], v[36:37]
	v_and_b32_e32 v31, 0xffff0000, v169
	v_pk_fma_f32 v[26:27], v[8:9], v[30:31], v[36:37]
	v_lshlrev_b32_e32 v31, 16, v170
	v_lshlrev_b32_e32 v30, 16, v166
	v_pk_fma_f32 v[26:27], v[10:11], v[30:31], v[26:27]
	v_and_b32_e32 v31, 0xffff0000, v170
	v_and_b32_e32 v30, 0xffff0000, v166
	v_pk_fma_f32 v[26:27], v[12:13], v[30:31], v[26:27]
	v_lshlrev_b32_e32 v31, 16, v171
	v_lshlrev_b32_e32 v30, 16, v167
	v_pk_fma_f32 v[26:27], v[14:15], v[30:31], v[26:27]
	v_and_b32_e32 v31, 0xffff0000, v171
	v_and_b32_e32 v30, 0xffff0000, v167
	v_pk_fma_f32 v[26:27], v[16:17], v[30:31], v[26:27]
	s_nop 0
	v_add_f32_e32 v23, v22, v26
	v_add_f32_e32 v23, v23, v27
	v_min_f32_e32 v25, 0, v23
	v_mul_f32_e64 v23, |v23|, s95
	v_exp_f32_e32 v23, v23
	s_nop 0
	v_add_f32_e32 v23, 1.0, v23
	v_cmp_gt_f32_e32 vcc, s34, v23
	s_nop 1
	v_cndmask_b32_e64 v26, 0, 32, vcc
	v_ldexp_f32 v23, v23, v26
	v_log_f32_e32 v23, v23
	s_nop 0
	v_mul_f32_e32 v26, 0x3f317217, v23
	v_fma_f32 v26, v23, s35, -v26
	v_fmac_f32_e32 v26, 0x3377d1cf, v23
	v_fmac_f32_e32 v26, 0x3f317217, v23
	v_cmp_lt_f32_e64 s[0:1], |v23|, s73
	s_nop 1
	v_cndmask_b32_e64 v23, v23, v26, s[0:1]
	v_cndmask_b32_e32 v26, 0, v210, vcc
	v_sub_f32_e32 v23, v23, v26
	v_sub_f32_e32 v23, v25, v23
	v_mul_f32_e32 v28, 0x3d800000, v23
	s_waitcnt vmcnt(0)
	v_and_b32_e32 v38, 0xffff0000, v52
	v_and_b32_e32 v39, 0xffff0000, v56
	v_lshlrev_b32_e32 v37, 16, v56
	v_lshlrev_b32_e32 v36, 16, v52
	v_pk_mul_f32 v[38:39], v[4:5], v[38:39]
	v_and_b32_e32 v30, 0xffff0000, v53
	v_pk_fma_f32 v[36:37], v[2:3], v[36:37], v[38:39]
	v_lshlrev_b32_e32 v39, 16, v57
	v_lshlrev_b32_e32 v38, 16, v53
	v_pk_fma_f32 v[36:37], v[6:7], v[38:39], v[36:37]
	v_and_b32_e32 v31, 0xffff0000, v57
	v_pk_fma_f32 v[26:27], v[8:9], v[30:31], v[36:37]
	v_lshlrev_b32_e32 v31, 16, v58
	v_lshlrev_b32_e32 v30, 16, v54
	v_pk_fma_f32 v[26:27], v[10:11], v[30:31], v[26:27]
	v_and_b32_e32 v31, 0xffff0000, v58
	v_and_b32_e32 v30, 0xffff0000, v54
	v_pk_fma_f32 v[26:27], v[12:13], v[30:31], v[26:27]
	v_lshlrev_b32_e32 v31, 16, v59
	v_lshlrev_b32_e32 v30, 16, v55
	v_pk_fma_f32 v[26:27], v[14:15], v[30:31], v[26:27]
	v_and_b32_e32 v31, 0xffff0000, v59
	v_and_b32_e32 v30, 0xffff0000, v55
	v_pk_fma_f32 v[26:27], v[16:17], v[30:31], v[26:27]
	s_nop 0
	v_add_f32_e32 v23, v22, v26
	v_add_f32_e32 v23, v23, v27
	v_min_f32_e32 v25, 0, v23
	v_mul_f32_e64 v23, |v23|, s95
	v_exp_f32_e32 v23, v23
	s_nop 0
	v_add_f32_e32 v23, 1.0, v23
	v_cmp_gt_f32_e32 vcc, s34, v23
	s_nop 1
	v_cndmask_b32_e64 v26, 0, 32, vcc
	v_ldexp_f32 v23, v23, v26
	v_log_f32_e32 v23, v23
	s_nop 0
	v_mul_f32_e32 v26, 0x3f317217, v23
	v_fma_f32 v26, v23, s35, -v26
	v_fmac_f32_e32 v26, 0x3377d1cf, v23
	v_fmac_f32_e32 v26, 0x3f317217, v23
	v_cmp_lt_f32_e64 s[0:1], |v23|, s73
	s_nop 1
	v_cndmask_b32_e64 v23, v23, v26, s[0:1]
	v_cndmask_b32_e32 v26, 0, v210, vcc
	v_sub_f32_e32 v23, v23, v26
	v_sub_f32_e32 v23, v25, v23
	v_mul_f32_e32 v29, 0x3d800000, v23
	ds_write2st64_b32 v0, v28, v29 offset0:8 offset1:12
	v_add_u32_e32 v0, 0x1000, v0
